# v110 + the nine GEMM inner-loop headers aligned to 64 bytes (s_nop fill)
# speedup vs baseline: 1.0076x; 1.0076x over previous
.LBB0_98:
	s_ashr_i32 s27, s26, 31
	s_lshl_b64 s[28:29], s[26:27], 20
	s_add_u32 s28, s97, s28
	s_addc_u32 s29, s33, s29
	s_and_b64 s[30:31], s[0:1], exec
	s_cselect_b32 s5, s29, s41
	s_cselect_b32 s27, s28, s40
	s_ashr_i32 s25, s24, 31
	s_lshl_b64 s[30:31], s[24:25], 20
	s_add_u32 s30, s6, s30
	s_addc_u32 s31, s7, s31
	s_and_b64 s[58:59], s[0:1], exec
	s_cselect_b32 s25, s31, s37
	s_cselect_b32 s35, s30, s36
	s_add_u32 s94, s40, 0x80080
	s_addc_u32 s95, s41, 0
	s_add_u32 s57, s36, 0x100
	v_mov_b32_e32 v2, 0
	s_addc_u32 s58, s37, 0
	s_mov_b32 s59, -2
	v_mov_b32_e32 v3, v2
	v_mov_b32_e32 v4, v2
	v_mov_b32_e32 v5, v2
	v_mov_b32_e32 v6, v2
	v_mov_b32_e32 v7, v2
	v_mov_b32_e32 v8, v2
	v_mov_b32_e32 v9, v2
	v_mov_b32_e32 v10, v2
	v_mov_b32_e32 v11, v2
	v_mov_b32_e32 v12, v2
	v_mov_b32_e32 v13, v2
	v_mov_b32_e32 v14, v2
	v_mov_b32_e32 v15, v2
	v_mov_b32_e32 v16, v2
	v_mov_b32_e32 v17, v2
	s_waitcnt vmcnt(0)
	v_mov_b32_e32 v18, v2
	v_mov_b32_e32 v19, v2
	v_mov_b32_e32 v20, v2
	v_mov_b32_e32 v21, v2
	v_mov_b32_e32 v22, v2
	v_mov_b32_e32 v23, v2
	v_mov_b32_e32 v24, v2
	v_mov_b32_e32 v25, v2
	v_mov_b32_e32 v26, v2
	v_mov_b32_e32 v27, v2
	v_mov_b32_e32 v28, v2
	v_mov_b32_e32 v29, v2
	v_mov_b32_e32 v30, v2
	v_mov_b32_e32 v31, v2
	v_mov_b32_e32 v32, v2
	v_mov_b32_e32 v33, v2
	v_mov_b32_e32 v66, v2
	v_mov_b32_e32 v67, v2
	v_mov_b32_e32 v68, v2
	v_mov_b32_e32 v69, v2
	v_mov_b32_e32 v70, v2
	v_mov_b32_e32 v71, v2
	v_mov_b32_e32 v72, v2
	v_mov_b32_e32 v73, v2
	v_mov_b32_e32 v74, v2
	v_mov_b32_e32 v75, v2
	v_mov_b32_e32 v76, v2
	v_mov_b32_e32 v77, v2
	v_mov_b32_e32 v78, v2
	v_mov_b32_e32 v79, v2
	v_mov_b32_e32 v80, v2
	v_mov_b32_e32 v81, v2
	v_mov_b32_e32 v82, v2
	v_mov_b32_e32 v83, v2
	v_mov_b32_e32 v84, v2
	v_mov_b32_e32 v85, v2
	v_mov_b32_e32 v86, v2
	v_mov_b32_e32 v87, v2
	v_mov_b32_e32 v88, v2
	v_mov_b32_e32 v89, v2
	v_mov_b32_e32 v90, v2
	v_mov_b32_e32 v91, v2
	v_mov_b32_e32 v92, v2
	v_mov_b32_e32 v93, v2
	v_mov_b32_e32 v94, v2
	v_mov_b32_e32 v95, v2
	v_mov_b32_e32 v96, v2
	v_mov_b32_e32 v97, v2
	v_mov_b32_e32 v34, v2
	v_mov_b32_e32 v35, v2
	v_mov_b32_e32 v36, v2
	v_mov_b32_e32 v37, v2
	v_mov_b32_e32 v38, v2
	v_mov_b32_e32 v39, v2
	v_mov_b32_e32 v40, v2
	v_mov_b32_e32 v41, v2
	v_mov_b32_e32 v42, v2
	v_mov_b32_e32 v43, v2
	v_mov_b32_e32 v44, v2
	v_mov_b32_e32 v45, v2
	v_mov_b32_e32 v46, v2
	v_mov_b32_e32 v47, v2
	v_mov_b32_e32 v48, v2
	v_mov_b32_e32 v49, v2
	v_mov_b32_e32 v50, v2
	v_mov_b32_e32 v51, v2
	v_mov_b32_e32 v52, v2
	v_mov_b32_e32 v53, v2
	v_mov_b32_e32 v54, v2
	v_mov_b32_e32 v55, v2
	v_mov_b32_e32 v56, v2
	v_mov_b32_e32 v57, v2
	v_mov_b32_e32 v58, v2
	v_mov_b32_e32 v59, v2
	v_mov_b32_e32 v60, v2
	v_mov_b32_e32 v61, v2
	v_mov_b32_e32 v62, v2
	v_mov_b32_e32 v63, v2
	v_mov_b32_e32 v64, v2
	v_mov_b32_e32 v65, v2
	v_mov_b32_e32 v98, v2
	v_mov_b32_e32 v99, v2
	v_mov_b32_e32 v100, v2
	v_mov_b32_e32 v101, v2
	v_mov_b32_e32 v102, v2
	v_mov_b32_e32 v103, v2
	v_mov_b32_e32 v104, v2
	v_mov_b32_e32 v105, v2
	v_mov_b32_e32 v106, v2
	v_mov_b32_e32 v107, v2
	v_mov_b32_e32 v108, v2
	v_mov_b32_e32 v109, v2
	v_mov_b32_e32 v110, v2
	v_mov_b32_e32 v111, v2
	v_mov_b32_e32 v112, v2
	v_mov_b32_e32 v113, v2
	v_mov_b32_e32 v114, v2
	v_mov_b32_e32 v115, v2
	v_mov_b32_e32 v116, v2
	v_mov_b32_e32 v117, v2
	v_mov_b32_e32 v118, v2
	v_mov_b32_e32 v119, v2
	v_mov_b32_e32 v120, v2
	v_mov_b32_e32 v121, v2
	v_mov_b32_e32 v122, v2
	v_mov_b32_e32 v123, v2
	v_mov_b32_e32 v124, v2
	v_mov_b32_e32 v125, v2
	v_mov_b32_e32 v126, v2
	v_mov_b32_e32 v127, v2
	v_mov_b32_e32 v128, v2
	v_mov_b32_e32 v129, v2
	.p2alignl 6, 3212836864

.LBB0_440:
	s_add_i32 s29, s53, -2
	s_add_u32 s94, s46, 0x80080
	s_addc_u32 s95, s47, 0
	s_add_u32 s31, s36, 0x100
	v_mov_b32_e32 v2, 0
	s_addc_u32 s35, s37, 0
	s_mov_b32 s36, 0
	v_mov_b32_e32 v3, v2
	v_mov_b32_e32 v4, v2
	v_mov_b32_e32 v5, v2
	v_mov_b32_e32 v6, v2
	v_mov_b32_e32 v7, v2
	v_mov_b32_e32 v8, v2
	v_mov_b32_e32 v9, v2
	v_mov_b32_e32 v10, v2
	v_mov_b32_e32 v11, v2
	v_mov_b32_e32 v12, v2
	v_mov_b32_e32 v13, v2
	v_mov_b32_e32 v14, v2
	v_mov_b32_e32 v15, v2
	v_mov_b32_e32 v16, v2
	v_mov_b32_e32 v17, v2
	v_mov_b32_e32 v18, v2
	v_mov_b32_e32 v19, v2
	v_mov_b32_e32 v20, v2
	v_mov_b32_e32 v21, v2
	v_mov_b32_e32 v22, v2
	v_mov_b32_e32 v23, v2
	v_mov_b32_e32 v24, v2
	v_mov_b32_e32 v25, v2
	v_mov_b32_e32 v26, v2
	v_mov_b32_e32 v27, v2
	v_mov_b32_e32 v28, v2
	v_mov_b32_e32 v29, v2
	v_mov_b32_e32 v30, v2
	v_mov_b32_e32 v31, v2
	v_mov_b32_e32 v32, v2
	v_mov_b32_e32 v33, v2
	v_mov_b32_e32 v70, v2
	v_mov_b32_e32 v71, v2
	v_mov_b32_e32 v72, v2
	v_mov_b32_e32 v73, v2
	v_mov_b32_e32 v74, v2
	v_mov_b32_e32 v75, v2
	v_mov_b32_e32 v76, v2
	v_mov_b32_e32 v77, v2
	v_mov_b32_e32 v78, v2
	v_mov_b32_e32 v79, v2
	v_mov_b32_e32 v80, v2
	v_mov_b32_e32 v81, v2
	v_mov_b32_e32 v82, v2
	v_mov_b32_e32 v83, v2
	v_mov_b32_e32 v84, v2
	v_mov_b32_e32 v85, v2
	v_mov_b32_e32 v86, v2
	v_mov_b32_e32 v87, v2
	v_mov_b32_e32 v88, v2
	v_mov_b32_e32 v89, v2
	v_mov_b32_e32 v90, v2
	v_mov_b32_e32 v91, v2
	v_mov_b32_e32 v92, v2
	v_mov_b32_e32 v93, v2
	v_mov_b32_e32 v94, v2
	v_mov_b32_e32 v95, v2
	v_mov_b32_e32 v96, v2
	v_mov_b32_e32 v97, v2
	v_mov_b32_e32 v34, v2
	v_mov_b32_e32 v35, v2
	v_mov_b32_e32 v36, v2
	v_mov_b32_e32 v37, v2
	v_mov_b32_e32 v98, v2
	v_mov_b32_e32 v99, v2
	v_mov_b32_e32 v100, v2
	v_mov_b32_e32 v101, v2
	v_mov_b32_e32 v38, v2
	v_mov_b32_e32 v39, v2
	v_mov_b32_e32 v40, v2
	v_mov_b32_e32 v41, v2
	v_mov_b32_e32 v42, v2
	v_mov_b32_e32 v43, v2
	v_mov_b32_e32 v44, v2
	v_mov_b32_e32 v45, v2
	v_mov_b32_e32 v46, v2
	v_mov_b32_e32 v47, v2
	v_mov_b32_e32 v48, v2
	v_mov_b32_e32 v49, v2
	v_mov_b32_e32 v50, v2
	v_mov_b32_e32 v51, v2
	v_mov_b32_e32 v52, v2
	v_mov_b32_e32 v53, v2
	v_mov_b32_e32 v54, v2
	v_mov_b32_e32 v55, v2
	v_mov_b32_e32 v56, v2
	v_mov_b32_e32 v57, v2
	v_mov_b32_e32 v58, v2
	v_mov_b32_e32 v59, v2
	v_mov_b32_e32 v60, v2
	v_mov_b32_e32 v61, v2
	v_mov_b32_e32 v62, v2
	v_mov_b32_e32 v63, v2
	v_mov_b32_e32 v64, v2
	v_mov_b32_e32 v65, v2
	v_mov_b32_e32 v102, v2
	v_mov_b32_e32 v103, v2
	v_mov_b32_e32 v104, v2
	v_mov_b32_e32 v105, v2
	v_mov_b32_e32 v106, v2
	v_mov_b32_e32 v107, v2
	v_mov_b32_e32 v108, v2
	v_mov_b32_e32 v109, v2
	v_mov_b32_e32 v110, v2
	v_mov_b32_e32 v111, v2
	v_mov_b32_e32 v112, v2
	v_mov_b32_e32 v113, v2
	v_mov_b32_e32 v114, v2
	v_mov_b32_e32 v115, v2
	v_mov_b32_e32 v116, v2
	v_mov_b32_e32 v117, v2
	v_mov_b32_e32 v118, v2
	v_mov_b32_e32 v119, v2
	v_mov_b32_e32 v120, v2
	v_mov_b32_e32 v121, v2
	v_mov_b32_e32 v122, v2
	v_mov_b32_e32 v123, v2
	v_mov_b32_e32 v124, v2
	v_mov_b32_e32 v125, v2
	v_mov_b32_e32 v126, v2
	v_mov_b32_e32 v127, v2
	v_mov_b32_e32 v128, v2
	v_mov_b32_e32 v129, v2
	v_mov_b32_e32 v66, v2
	v_mov_b32_e32 v67, v2
	v_mov_b32_e32 v68, v2
	v_mov_b32_e32 v69, v2
	.p2alignl 6, 3212836864

.LBB0_614:
	s_ashr_i32 s23, s22, 31
	s_lshl_b64 s[24:25], s[22:23], 20
	s_add_u32 s24, s97, s24
	s_addc_u32 s25, s33, s25
	s_and_b64 s[26:27], s[0:1], exec
	s_cselect_b32 s23, s25, s31
	s_cselect_b32 s62, s24, s30
	s_ashr_i32 s21, s20, 31
	s_lshl_b64 s[26:27], s[20:21], 20
	s_add_u32 s26, s6, s26
	s_addc_u32 s27, s7, s27
	s_and_b64 s[36:37], s[0:1], exec
	s_cselect_b32 s21, s27, s35
	s_cselect_b32 s63, s26, s34
	s_add_u32 s30, s30, 0x80080
	s_addc_u32 s31, s31, 0
	s_add_u32 s66, s34, 0x100
	v_mov_b32_e32 v2, 0
	s_addc_u32 s67, s35, 0
	s_mov_b32 s76, -2
	v_mov_b32_e32 v3, v2
	v_mov_b32_e32 v4, v2
	v_mov_b32_e32 v5, v2
	v_mov_b32_e32 v6, v2
	v_mov_b32_e32 v7, v2
	v_mov_b32_e32 v8, v2
	v_mov_b32_e32 v9, v2
	v_mov_b32_e32 v18, v2
	v_mov_b32_e32 v19, v2
	v_mov_b32_e32 v20, v2
	v_mov_b32_e32 v21, v2
	v_mov_b32_e32 v22, v2
	v_mov_b32_e32 v23, v2
	v_mov_b32_e32 v24, v2
	v_mov_b32_e32 v25, v2
	v_mov_b32_e32 v34, v2
	v_mov_b32_e32 v35, v2
	v_mov_b32_e32 v36, v2
	v_mov_b32_e32 v37, v2
	v_mov_b32_e32 v38, v2
	v_mov_b32_e32 v39, v2
	v_mov_b32_e32 v40, v2
	v_mov_b32_e32 v41, v2
	v_mov_b32_e32 v50, v2
	v_mov_b32_e32 v51, v2
	v_mov_b32_e32 v52, v2
	v_mov_b32_e32 v53, v2
	v_mov_b32_e32 v54, v2
	v_mov_b32_e32 v55, v2
	v_mov_b32_e32 v56, v2
	v_mov_b32_e32 v57, v2
	v_mov_b32_e32 v10, v2
	v_mov_b32_e32 v11, v2
	v_mov_b32_e32 v12, v2
	v_mov_b32_e32 v13, v2
	v_mov_b32_e32 v14, v2
	v_mov_b32_e32 v15, v2
	v_mov_b32_e32 v16, v2
	v_mov_b32_e32 v17, v2
	v_mov_b32_e32 v26, v2
	v_mov_b32_e32 v27, v2
	v_mov_b32_e32 v28, v2
	v_mov_b32_e32 v29, v2
	v_mov_b32_e32 v30, v2
	v_mov_b32_e32 v31, v2
	v_mov_b32_e32 v32, v2
	v_mov_b32_e32 v33, v2
	v_mov_b32_e32 v42, v2
	v_mov_b32_e32 v43, v2
	v_mov_b32_e32 v44, v2
	v_mov_b32_e32 v45, v2
	v_mov_b32_e32 v46, v2
	v_mov_b32_e32 v47, v2
	v_mov_b32_e32 v48, v2
	v_mov_b32_e32 v49, v2
	v_mov_b32_e32 v58, v2
	v_mov_b32_e32 v59, v2
	v_mov_b32_e32 v60, v2
	v_mov_b32_e32 v61, v2
	v_mov_b32_e32 v62, v2
	v_mov_b32_e32 v63, v2
	v_mov_b32_e32 v64, v2
	v_mov_b32_e32 v65, v2
	v_mov_b32_e32 v66, v2
	v_mov_b32_e32 v67, v2
	v_mov_b32_e32 v68, v2
	v_mov_b32_e32 v69, v2
	v_mov_b32_e32 v70, v2
	v_mov_b32_e32 v71, v2
	v_mov_b32_e32 v72, v2
	v_mov_b32_e32 v73, v2
	v_mov_b32_e32 v82, v2
	v_mov_b32_e32 v83, v2
	v_mov_b32_e32 v84, v2
	v_mov_b32_e32 v85, v2
	v_mov_b32_e32 v86, v2
	v_mov_b32_e32 v87, v2
	v_mov_b32_e32 v88, v2
	v_mov_b32_e32 v89, v2
	v_mov_b32_e32 v98, v2
	v_mov_b32_e32 v99, v2
	v_mov_b32_e32 v100, v2
	v_mov_b32_e32 v101, v2
	v_mov_b32_e32 v102, v2
	v_mov_b32_e32 v103, v2
	v_mov_b32_e32 v104, v2
	v_mov_b32_e32 v105, v2
	v_mov_b32_e32 v114, v2
	v_mov_b32_e32 v115, v2
	v_mov_b32_e32 v116, v2
	v_mov_b32_e32 v117, v2
	v_mov_b32_e32 v118, v2
	v_mov_b32_e32 v119, v2
	v_mov_b32_e32 v120, v2
	v_mov_b32_e32 v121, v2
	v_mov_b32_e32 v74, v2
	v_mov_b32_e32 v75, v2
	v_mov_b32_e32 v76, v2
	v_mov_b32_e32 v77, v2
	v_mov_b32_e32 v78, v2
	v_mov_b32_e32 v79, v2
	v_mov_b32_e32 v80, v2
	v_mov_b32_e32 v81, v2
	v_mov_b32_e32 v90, v2
	v_mov_b32_e32 v91, v2
	v_mov_b32_e32 v92, v2
	v_mov_b32_e32 v93, v2
	v_mov_b32_e32 v94, v2
	v_mov_b32_e32 v95, v2
	v_mov_b32_e32 v96, v2
	v_mov_b32_e32 v97, v2
	v_mov_b32_e32 v106, v2
	v_mov_b32_e32 v107, v2
	v_mov_b32_e32 v108, v2
	v_mov_b32_e32 v109, v2
	v_mov_b32_e32 v110, v2
	v_mov_b32_e32 v111, v2
	v_mov_b32_e32 v112, v2
	v_mov_b32_e32 v113, v2
	v_mov_b32_e32 v122, v2
	v_mov_b32_e32 v123, v2
	v_mov_b32_e32 v124, v2
	v_mov_b32_e32 v125, v2
	v_mov_b32_e32 v126, v2
	v_mov_b32_e32 v127, v2
	v_mov_b32_e32 v128, v2
	v_mov_b32_e32 v129, v2
	.p2alignl 6, 3212836864

.LBB0_701:
	s_add_i32 s25, s47, -2
	s_add_u32 s30, s30, 0x160080
	s_addc_u32 s31, s31, 0
	s_add_u32 s53, s34, 0x100
	v_mov_b32_e32 v2, 0
	s_addc_u32 s78, s35, 0
	s_mov_b32 s34, 0
	v_mov_b32_e32 v3, v2
	v_mov_b32_e32 v4, v2
	v_mov_b32_e32 v5, v2
	v_mov_b32_e32 v6, v2
	v_mov_b32_e32 v7, v2
	v_mov_b32_e32 v8, v2
	v_mov_b32_e32 v9, v2
	v_mov_b32_e32 v10, v2
	v_mov_b32_e32 v11, v2
	v_mov_b32_e32 v12, v2
	v_mov_b32_e32 v13, v2
	v_mov_b32_e32 v14, v2
	v_mov_b32_e32 v15, v2
	v_mov_b32_e32 v16, v2
	v_mov_b32_e32 v17, v2
	v_mov_b32_e32 v18, v2
	v_mov_b32_e32 v19, v2
	v_mov_b32_e32 v20, v2
	v_mov_b32_e32 v21, v2
	v_mov_b32_e32 v22, v2
	v_mov_b32_e32 v23, v2
	v_mov_b32_e32 v24, v2
	v_mov_b32_e32 v25, v2
	v_mov_b32_e32 v26, v2
	v_mov_b32_e32 v27, v2
	v_mov_b32_e32 v28, v2
	v_mov_b32_e32 v29, v2
	v_mov_b32_e32 v30, v2
	v_mov_b32_e32 v31, v2
	v_mov_b32_e32 v32, v2
	v_mov_b32_e32 v33, v2
	v_mov_b32_e32 v70, v2
	v_mov_b32_e32 v71, v2
	v_mov_b32_e32 v72, v2
	v_mov_b32_e32 v73, v2
	v_mov_b32_e32 v74, v2
	v_mov_b32_e32 v75, v2
	v_mov_b32_e32 v76, v2
	v_mov_b32_e32 v77, v2
	v_mov_b32_e32 v78, v2
	v_mov_b32_e32 v79, v2
	v_mov_b32_e32 v80, v2
	v_mov_b32_e32 v81, v2
	v_mov_b32_e32 v82, v2
	v_mov_b32_e32 v83, v2
	v_mov_b32_e32 v84, v2
	v_mov_b32_e32 v85, v2
	v_mov_b32_e32 v86, v2
	v_mov_b32_e32 v87, v2
	v_mov_b32_e32 v88, v2
	v_mov_b32_e32 v89, v2
	v_mov_b32_e32 v90, v2
	v_mov_b32_e32 v91, v2
	v_mov_b32_e32 v92, v2
	v_mov_b32_e32 v93, v2
	v_mov_b32_e32 v94, v2
	v_mov_b32_e32 v95, v2
	v_mov_b32_e32 v96, v2
	v_mov_b32_e32 v97, v2
	v_mov_b32_e32 v34, v2
	v_mov_b32_e32 v35, v2
	v_mov_b32_e32 v36, v2
	v_mov_b32_e32 v37, v2
	v_mov_b32_e32 v98, v2
	v_mov_b32_e32 v99, v2
	v_mov_b32_e32 v100, v2
	v_mov_b32_e32 v101, v2
	v_mov_b32_e32 v38, v2
	v_mov_b32_e32 v39, v2
	v_mov_b32_e32 v40, v2
	v_mov_b32_e32 v41, v2
	v_mov_b32_e32 v42, v2
	v_mov_b32_e32 v43, v2
	v_mov_b32_e32 v44, v2
	v_mov_b32_e32 v45, v2
	v_mov_b32_e32 v46, v2
	v_mov_b32_e32 v47, v2
	v_mov_b32_e32 v48, v2
	v_mov_b32_e32 v49, v2
	v_mov_b32_e32 v50, v2
	v_mov_b32_e32 v51, v2
	v_mov_b32_e32 v52, v2
	v_mov_b32_e32 v53, v2
	v_mov_b32_e32 v54, v2
	v_mov_b32_e32 v55, v2
	v_mov_b32_e32 v56, v2
	v_mov_b32_e32 v57, v2
	v_mov_b32_e32 v58, v2
	v_mov_b32_e32 v59, v2
	v_mov_b32_e32 v60, v2
	v_mov_b32_e32 v61, v2
	v_mov_b32_e32 v62, v2
	v_mov_b32_e32 v63, v2
	v_mov_b32_e32 v64, v2
	v_mov_b32_e32 v65, v2
	v_mov_b32_e32 v102, v2
	v_mov_b32_e32 v103, v2
	v_mov_b32_e32 v104, v2
	v_mov_b32_e32 v105, v2
	v_mov_b32_e32 v106, v2
	v_mov_b32_e32 v107, v2
	v_mov_b32_e32 v108, v2
	v_mov_b32_e32 v109, v2
	v_mov_b32_e32 v110, v2
	v_mov_b32_e32 v111, v2
	v_mov_b32_e32 v112, v2
	v_mov_b32_e32 v113, v2
	v_mov_b32_e32 v114, v2
	v_mov_b32_e32 v115, v2
	v_mov_b32_e32 v116, v2
	v_mov_b32_e32 v117, v2
	v_mov_b32_e32 v118, v2
	v_mov_b32_e32 v119, v2
	v_mov_b32_e32 v120, v2
	v_mov_b32_e32 v121, v2
	v_mov_b32_e32 v122, v2
	v_mov_b32_e32 v123, v2
	v_mov_b32_e32 v124, v2
	v_mov_b32_e32 v125, v2
	v_mov_b32_e32 v126, v2
	v_mov_b32_e32 v127, v2
	v_mov_b32_e32 v128, v2
	v_mov_b32_e32 v129, v2
	v_mov_b32_e32 v66, v2
	v_mov_b32_e32 v67, v2
	v_mov_b32_e32 v68, v2
	v_mov_b32_e32 v69, v2
	.p2alignl 6, 3212836864

.LBB0_879:
	s_ashr_i32 s31, s30, 31
	s_lshl_b64 s[34:35], s[30:31], 20
	s_add_u32 s34, s38, s34
	s_addc_u32 s35, s39, s35
	s_and_b64 s[56:57], s[6:7], exec
	s_cselect_b32 s9, s35, s11
	s_cselect_b32 s31, s34, s10
	s_ashr_i32 s29, s28, 31
	s_lshl_b64 s[56:57], s[28:29], 20
	s_add_u32 s56, s16, s56
	s_addc_u32 s57, s17, s57
	s_and_b64 s[58:59], s[6:7], exec
	s_cselect_b32 s29, s57, s37
	s_cselect_b32 s62, s56, s36
	s_add_u32 s10, s10, 0x80080
	s_addc_u32 s11, s11, 0
	s_add_u32 s63, s36, 0x100
	v_mov_b32_e32 v2, 0
	s_addc_u32 s78, s37, 0
	s_mov_b32 s79, -2
	v_mov_b32_e32 v3, v2
	v_mov_b32_e32 v4, v2
	v_mov_b32_e32 v5, v2
	v_mov_b32_e32 v6, v2
	v_mov_b32_e32 v7, v2
	v_mov_b32_e32 v8, v2
	v_mov_b32_e32 v9, v2
	v_mov_b32_e32 v18, v2
	v_mov_b32_e32 v19, v2
	v_mov_b32_e32 v20, v2
	v_mov_b32_e32 v21, v2
	v_mov_b32_e32 v22, v2
	v_mov_b32_e32 v23, v2
	v_mov_b32_e32 v24, v2
	v_mov_b32_e32 v25, v2
	v_mov_b32_e32 v34, v2
	v_mov_b32_e32 v35, v2
	v_mov_b32_e32 v36, v2
	v_mov_b32_e32 v37, v2
	v_mov_b32_e32 v38, v2
	v_mov_b32_e32 v39, v2
	v_mov_b32_e32 v40, v2
	v_mov_b32_e32 v41, v2
	v_mov_b32_e32 v50, v2
	v_mov_b32_e32 v51, v2
	v_mov_b32_e32 v52, v2
	v_mov_b32_e32 v53, v2
	v_mov_b32_e32 v54, v2
	v_mov_b32_e32 v55, v2
	v_mov_b32_e32 v56, v2
	v_mov_b32_e32 v57, v2
	v_mov_b32_e32 v10, v2
	v_mov_b32_e32 v11, v2
	v_mov_b32_e32 v12, v2
	v_mov_b32_e32 v13, v2
	v_mov_b32_e32 v14, v2
	v_mov_b32_e32 v15, v2
	v_mov_b32_e32 v16, v2
	v_mov_b32_e32 v17, v2
	v_mov_b32_e32 v26, v2
	v_mov_b32_e32 v27, v2
	v_mov_b32_e32 v28, v2
	v_mov_b32_e32 v29, v2
	v_mov_b32_e32 v30, v2
	v_mov_b32_e32 v31, v2
	v_mov_b32_e32 v32, v2
	v_mov_b32_e32 v33, v2
	v_mov_b32_e32 v42, v2
	v_mov_b32_e32 v43, v2
	v_mov_b32_e32 v44, v2
	v_mov_b32_e32 v45, v2
	v_mov_b32_e32 v46, v2
	v_mov_b32_e32 v47, v2
	v_mov_b32_e32 v48, v2
	v_mov_b32_e32 v49, v2
	v_mov_b32_e32 v58, v2
	v_mov_b32_e32 v59, v2
	v_mov_b32_e32 v60, v2
	v_mov_b32_e32 v61, v2
	v_mov_b32_e32 v62, v2
	v_mov_b32_e32 v63, v2
	v_mov_b32_e32 v64, v2
	v_mov_b32_e32 v65, v2
	v_mov_b32_e32 v66, v2
	v_mov_b32_e32 v67, v2
	v_mov_b32_e32 v68, v2
	v_mov_b32_e32 v69, v2
	v_mov_b32_e32 v70, v2
	v_mov_b32_e32 v71, v2
	v_mov_b32_e32 v72, v2
	v_mov_b32_e32 v73, v2
	v_mov_b32_e32 v82, v2
	v_mov_b32_e32 v83, v2
	v_mov_b32_e32 v84, v2
	v_mov_b32_e32 v85, v2
	v_mov_b32_e32 v86, v2
	v_mov_b32_e32 v87, v2
	v_mov_b32_e32 v88, v2
	v_mov_b32_e32 v89, v2
	v_mov_b32_e32 v98, v2
	v_mov_b32_e32 v99, v2
	v_mov_b32_e32 v100, v2
	v_mov_b32_e32 v101, v2
	v_mov_b32_e32 v102, v2
	v_mov_b32_e32 v103, v2
	v_mov_b32_e32 v104, v2
	v_mov_b32_e32 v105, v2
	v_mov_b32_e32 v114, v2
	v_mov_b32_e32 v115, v2
	v_mov_b32_e32 v116, v2
	v_mov_b32_e32 v117, v2
	v_mov_b32_e32 v118, v2
	v_mov_b32_e32 v119, v2
	v_mov_b32_e32 v120, v2
	v_mov_b32_e32 v121, v2
	v_mov_b32_e32 v74, v2
	v_mov_b32_e32 v75, v2
	v_mov_b32_e32 v76, v2
	v_mov_b32_e32 v77, v2
	v_mov_b32_e32 v78, v2
	v_mov_b32_e32 v79, v2
	v_mov_b32_e32 v80, v2
	v_mov_b32_e32 v81, v2
	v_mov_b32_e32 v90, v2
	v_mov_b32_e32 v91, v2
	v_mov_b32_e32 v92, v2
	v_mov_b32_e32 v93, v2
	v_mov_b32_e32 v94, v2
	v_mov_b32_e32 v95, v2
	v_mov_b32_e32 v96, v2
	v_mov_b32_e32 v97, v2
	v_mov_b32_e32 v106, v2
	v_mov_b32_e32 v107, v2
	v_mov_b32_e32 v108, v2
	v_mov_b32_e32 v109, v2
	v_mov_b32_e32 v110, v2
	v_mov_b32_e32 v111, v2
	v_mov_b32_e32 v112, v2
	v_mov_b32_e32 v113, v2
	v_mov_b32_e32 v122, v2
	v_mov_b32_e32 v123, v2
	v_mov_b32_e32 v124, v2
	v_mov_b32_e32 v125, v2
	v_mov_b32_e32 v126, v2
	v_mov_b32_e32 v127, v2
	v_mov_b32_e32 v128, v2
	v_mov_b32_e32 v129, v2
	.p2alignl 6, 3212836864

.LBB0_994:
	s_ashr_i32 s29, s28, 31
	s_lshl_b64 s[30:31], s[28:29], 20
	s_add_u32 s30, s97, s30
	s_addc_u32 s31, s33, s31
	s_and_b64 s[34:35], s[6:7], exec
	s_cselect_b32 s29, s31, s9
	s_cselect_b32 s57, s30, s8
	s_ashr_i32 s27, s26, 31
	s_lshl_b64 s[34:35], s[26:27], 20
	s_add_u32 s34, s14, s34
	s_addc_u32 s35, s15, s35
	s_and_b64 s[58:59], s[6:7], exec
	s_cselect_b32 s27, s35, s37
	s_cselect_b32 s80, s34, s36
	s_add_u32 s8, s8, 0x80080
	s_addc_u32 s9, s9, 0
	s_add_u32 s81, s36, 0x100
	v_mov_b32_e32 v2, 0
	s_addc_u32 s82, s37, 0
	s_mov_b32 s83, -2
	v_mov_b32_e32 v3, v2
	v_mov_b32_e32 v4, v2
	v_mov_b32_e32 v5, v2
	v_mov_b32_e32 v6, v2
	v_mov_b32_e32 v7, v2
	v_mov_b32_e32 v8, v2
	v_mov_b32_e32 v9, v2
	v_mov_b32_e32 v18, v2
	v_mov_b32_e32 v19, v2
	v_mov_b32_e32 v20, v2
	v_mov_b32_e32 v21, v2
	v_mov_b32_e32 v22, v2
	v_mov_b32_e32 v23, v2
	v_mov_b32_e32 v24, v2
	v_mov_b32_e32 v25, v2
	v_mov_b32_e32 v34, v2
	v_mov_b32_e32 v35, v2
	v_mov_b32_e32 v36, v2
	v_mov_b32_e32 v37, v2
	v_mov_b32_e32 v38, v2
	v_mov_b32_e32 v39, v2
	v_mov_b32_e32 v40, v2
	v_mov_b32_e32 v41, v2
	v_mov_b32_e32 v50, v2
	v_mov_b32_e32 v51, v2
	v_mov_b32_e32 v52, v2
	v_mov_b32_e32 v53, v2
	v_mov_b32_e32 v54, v2
	v_mov_b32_e32 v55, v2
	v_mov_b32_e32 v56, v2
	v_mov_b32_e32 v57, v2
	v_mov_b32_e32 v10, v2
	v_mov_b32_e32 v11, v2
	v_mov_b32_e32 v12, v2
	v_mov_b32_e32 v13, v2
	v_mov_b32_e32 v14, v2
	v_mov_b32_e32 v15, v2
	v_mov_b32_e32 v16, v2
	v_mov_b32_e32 v17, v2
	v_mov_b32_e32 v26, v2
	v_mov_b32_e32 v27, v2
	v_mov_b32_e32 v28, v2
	v_mov_b32_e32 v29, v2
	v_mov_b32_e32 v30, v2
	v_mov_b32_e32 v31, v2
	v_mov_b32_e32 v32, v2
	v_mov_b32_e32 v33, v2
	v_mov_b32_e32 v42, v2
	v_mov_b32_e32 v43, v2
	v_mov_b32_e32 v44, v2
	v_mov_b32_e32 v45, v2
	v_mov_b32_e32 v46, v2
	v_mov_b32_e32 v47, v2
	v_mov_b32_e32 v48, v2
	v_mov_b32_e32 v49, v2
	v_mov_b32_e32 v58, v2
	v_mov_b32_e32 v59, v2
	v_mov_b32_e32 v60, v2
	v_mov_b32_e32 v61, v2
	v_mov_b32_e32 v62, v2
	v_mov_b32_e32 v63, v2
	v_mov_b32_e32 v64, v2
	v_mov_b32_e32 v65, v2
	v_mov_b32_e32 v66, v2
	v_mov_b32_e32 v67, v2
	v_mov_b32_e32 v68, v2
	v_mov_b32_e32 v69, v2
	v_mov_b32_e32 v70, v2
	v_mov_b32_e32 v71, v2
	v_mov_b32_e32 v72, v2
	v_mov_b32_e32 v73, v2
	v_mov_b32_e32 v82, v2
	v_mov_b32_e32 v83, v2
	v_mov_b32_e32 v84, v2
	v_mov_b32_e32 v85, v2
	v_mov_b32_e32 v86, v2
	v_mov_b32_e32 v87, v2
	v_mov_b32_e32 v88, v2
	v_mov_b32_e32 v89, v2
	v_mov_b32_e32 v98, v2
	v_mov_b32_e32 v99, v2
	v_mov_b32_e32 v100, v2
	v_mov_b32_e32 v101, v2
	v_mov_b32_e32 v102, v2
	v_mov_b32_e32 v103, v2
	v_mov_b32_e32 v104, v2
	v_mov_b32_e32 v105, v2
	v_mov_b32_e32 v114, v2
	v_mov_b32_e32 v115, v2
	v_mov_b32_e32 v116, v2
	v_mov_b32_e32 v117, v2
	v_mov_b32_e32 v118, v2
	v_mov_b32_e32 v119, v2
	v_mov_b32_e32 v120, v2
	v_mov_b32_e32 v121, v2
	v_mov_b32_e32 v74, v2
	v_mov_b32_e32 v75, v2
	v_mov_b32_e32 v76, v2
	v_mov_b32_e32 v77, v2
	v_mov_b32_e32 v78, v2
	v_mov_b32_e32 v79, v2
	v_mov_b32_e32 v80, v2
	v_mov_b32_e32 v81, v2
	v_mov_b32_e32 v90, v2
	v_mov_b32_e32 v91, v2
	v_mov_b32_e32 v92, v2
	v_mov_b32_e32 v93, v2
	v_mov_b32_e32 v94, v2
	v_mov_b32_e32 v95, v2
	v_mov_b32_e32 v96, v2
	v_mov_b32_e32 v97, v2
	v_mov_b32_e32 v106, v2
	v_mov_b32_e32 v107, v2
	v_mov_b32_e32 v108, v2
	v_mov_b32_e32 v109, v2
	v_mov_b32_e32 v110, v2
	v_mov_b32_e32 v111, v2
	v_mov_b32_e32 v112, v2
	v_mov_b32_e32 v113, v2
	v_mov_b32_e32 v122, v2
	v_mov_b32_e32 v123, v2
	v_mov_b32_e32 v124, v2
	v_mov_b32_e32 v125, v2
	v_mov_b32_e32 v126, v2
	v_mov_b32_e32 v127, v2
	v_mov_b32_e32 v128, v2
	v_mov_b32_e32 v129, v2
	.p2alignl 6, 3212836864

.LBB0_1258:
	s_add_i32 s19, s54, -2
	s_add_u32 s48, s48, 0x80080
	s_addc_u32 s49, s49, 0
	s_add_u32 s21, s36, 0x100
	v_mov_b32_e32 v2, 0
	s_addc_u32 s23, s37, 0
	s_mov_b32 s36, 0
	v_mov_b32_e32 v3, v2
	v_mov_b32_e32 v4, v2
	v_mov_b32_e32 v5, v2
	v_mov_b32_e32 v6, v2
	v_mov_b32_e32 v7, v2
	v_mov_b32_e32 v8, v2
	v_mov_b32_e32 v9, v2
	v_mov_b32_e32 v10, v2
	v_mov_b32_e32 v11, v2
	v_mov_b32_e32 v12, v2
	v_mov_b32_e32 v13, v2
	v_mov_b32_e32 v14, v2
	v_mov_b32_e32 v15, v2
	v_mov_b32_e32 v16, v2
	v_mov_b32_e32 v17, v2
	v_mov_b32_e32 v18, v2
	v_mov_b32_e32 v19, v2
	v_mov_b32_e32 v20, v2
	v_mov_b32_e32 v21, v2
	v_mov_b32_e32 v22, v2
	v_mov_b32_e32 v23, v2
	v_mov_b32_e32 v24, v2
	v_mov_b32_e32 v25, v2
	v_mov_b32_e32 v26, v2
	v_mov_b32_e32 v27, v2
	v_mov_b32_e32 v28, v2
	v_mov_b32_e32 v29, v2
	v_mov_b32_e32 v30, v2
	v_mov_b32_e32 v31, v2
	v_mov_b32_e32 v32, v2
	v_mov_b32_e32 v33, v2
	v_mov_b32_e32 v70, v2
	v_mov_b32_e32 v71, v2
	v_mov_b32_e32 v72, v2
	v_mov_b32_e32 v73, v2
	v_mov_b32_e32 v74, v2
	v_mov_b32_e32 v75, v2
	v_mov_b32_e32 v76, v2
	v_mov_b32_e32 v77, v2
	v_mov_b32_e32 v78, v2
	v_mov_b32_e32 v79, v2
	v_mov_b32_e32 v80, v2
	v_mov_b32_e32 v81, v2
	v_mov_b32_e32 v82, v2
	v_mov_b32_e32 v83, v2
	v_mov_b32_e32 v84, v2
	v_mov_b32_e32 v85, v2
	v_mov_b32_e32 v86, v2
	v_mov_b32_e32 v87, v2
	v_mov_b32_e32 v88, v2
	v_mov_b32_e32 v89, v2
	v_mov_b32_e32 v90, v2
	v_mov_b32_e32 v91, v2
	v_mov_b32_e32 v92, v2
	v_mov_b32_e32 v93, v2
	v_mov_b32_e32 v94, v2
	v_mov_b32_e32 v95, v2
	v_mov_b32_e32 v96, v2
	v_mov_b32_e32 v97, v2
	v_mov_b32_e32 v34, v2
	v_mov_b32_e32 v35, v2
	v_mov_b32_e32 v36, v2
	v_mov_b32_e32 v37, v2
	v_mov_b32_e32 v98, v2
	v_mov_b32_e32 v99, v2
	v_mov_b32_e32 v100, v2
	v_mov_b32_e32 v101, v2
	v_mov_b32_e32 v38, v2
	v_mov_b32_e32 v39, v2
	v_mov_b32_e32 v40, v2
	v_mov_b32_e32 v41, v2
	v_mov_b32_e32 v42, v2
	v_mov_b32_e32 v43, v2
	v_mov_b32_e32 v44, v2
	v_mov_b32_e32 v45, v2
	v_mov_b32_e32 v46, v2
	v_mov_b32_e32 v47, v2
	v_mov_b32_e32 v48, v2
	v_mov_b32_e32 v49, v2
	v_mov_b32_e32 v50, v2
	v_mov_b32_e32 v51, v2
	v_mov_b32_e32 v52, v2
	v_mov_b32_e32 v53, v2
	v_mov_b32_e32 v54, v2
	s_waitcnt lgkmcnt(0)
	v_mov_b32_e32 v55, v2
	v_mov_b32_e32 v56, v2
	v_mov_b32_e32 v57, v2
	v_mov_b32_e32 v58, v2
	v_mov_b32_e32 v59, v2
	v_mov_b32_e32 v60, v2
	v_mov_b32_e32 v61, v2
	v_mov_b32_e32 v62, v2
	v_mov_b32_e32 v63, v2
	v_mov_b32_e32 v64, v2
	v_mov_b32_e32 v65, v2
	v_mov_b32_e32 v102, v2
	v_mov_b32_e32 v103, v2
	v_mov_b32_e32 v104, v2
	v_mov_b32_e32 v105, v2
	v_mov_b32_e32 v106, v2
	v_mov_b32_e32 v107, v2
	v_mov_b32_e32 v108, v2
	v_mov_b32_e32 v109, v2
	v_mov_b32_e32 v110, v2
	v_mov_b32_e32 v111, v2
	v_mov_b32_e32 v112, v2
	v_mov_b32_e32 v113, v2
	v_mov_b32_e32 v114, v2
	v_mov_b32_e32 v115, v2
	v_mov_b32_e32 v116, v2
	v_mov_b32_e32 v117, v2
	v_mov_b32_e32 v118, v2
	v_mov_b32_e32 v119, v2
	v_mov_b32_e32 v120, v2
	v_mov_b32_e32 v121, v2
	v_mov_b32_e32 v122, v2
	v_mov_b32_e32 v123, v2
	v_mov_b32_e32 v124, v2
	v_mov_b32_e32 v125, v2
	v_mov_b32_e32 v126, v2
	v_mov_b32_e32 v127, v2
	v_mov_b32_e32 v128, v2
	v_mov_b32_e32 v129, v2
	v_mov_b32_e32 v66, v2
	v_mov_b32_e32 v67, v2
	v_mov_b32_e32 v68, v2
	v_mov_b32_e32 v69, v2
	.p2alignl 6, 3212836864

.LBB0_1426:
	s_ashr_i32 s15, s14, 31
	s_lshl_b64 s[16:17], s[14:15], 20
	s_add_u32 s16, s97, s16
	s_addc_u32 s17, s33, s17
	s_and_b64 s[18:19], s[0:1], exec
	s_cselect_b32 s15, s17, s23
	s_cselect_b32 s50, s16, s22
	s_ashr_i32 s13, s12, 31
	s_lshl_b64 s[18:19], s[12:13], 20
	s_add_u32 s18, s52, s18
	s_addc_u32 s19, s53, s19
	s_and_b64 s[26:27], s[0:1], exec
	s_cselect_b32 s13, s19, s25
	s_cselect_b32 s51, s18, s24
	s_add_u32 s22, s22, 0x80080
	s_addc_u32 s23, s23, 0
	s_add_u32 s54, s24, 0x100
	v_mov_b32_e32 v2, 0
	s_addc_u32 s55, s25, 0
	s_mov_b32 s56, -2
	v_mov_b32_e32 v3, v2
	v_mov_b32_e32 v4, v2
	v_mov_b32_e32 v5, v2
	v_mov_b32_e32 v6, v2
	v_mov_b32_e32 v7, v2
	v_mov_b32_e32 v8, v2
	v_mov_b32_e32 v9, v2
	v_mov_b32_e32 v18, v2
	v_mov_b32_e32 v19, v2
	v_mov_b32_e32 v20, v2
	v_mov_b32_e32 v21, v2
	v_mov_b32_e32 v22, v2
	v_mov_b32_e32 v23, v2
	v_mov_b32_e32 v24, v2
	v_mov_b32_e32 v25, v2
	v_mov_b32_e32 v34, v2
	v_mov_b32_e32 v35, v2
	v_mov_b32_e32 v36, v2
	v_mov_b32_e32 v37, v2
	v_mov_b32_e32 v38, v2
	v_mov_b32_e32 v39, v2
	v_mov_b32_e32 v40, v2
	v_mov_b32_e32 v41, v2
	v_mov_b32_e32 v50, v2
	v_mov_b32_e32 v51, v2
	v_mov_b32_e32 v52, v2
	v_mov_b32_e32 v53, v2
	v_mov_b32_e32 v54, v2
	s_waitcnt lgkmcnt(0)
	v_mov_b32_e32 v55, v2
	v_mov_b32_e32 v56, v2
	v_mov_b32_e32 v57, v2
	v_mov_b32_e32 v10, v2
	v_mov_b32_e32 v11, v2
	v_mov_b32_e32 v12, v2
	v_mov_b32_e32 v13, v2
	v_mov_b32_e32 v14, v2
	v_mov_b32_e32 v15, v2
	v_mov_b32_e32 v16, v2
	v_mov_b32_e32 v17, v2
	v_mov_b32_e32 v26, v2
	v_mov_b32_e32 v27, v2
	v_mov_b32_e32 v28, v2
	v_mov_b32_e32 v29, v2
	v_mov_b32_e32 v30, v2
	v_mov_b32_e32 v31, v2
	v_mov_b32_e32 v32, v2
	v_mov_b32_e32 v33, v2
	v_mov_b32_e32 v42, v2
	v_mov_b32_e32 v43, v2
	v_mov_b32_e32 v44, v2
	v_mov_b32_e32 v45, v2
	v_mov_b32_e32 v46, v2
	v_mov_b32_e32 v47, v2
	v_mov_b32_e32 v48, v2
	v_mov_b32_e32 v49, v2
	v_mov_b32_e32 v58, v2
	v_mov_b32_e32 v59, v2
	v_mov_b32_e32 v60, v2
	v_mov_b32_e32 v61, v2
	v_mov_b32_e32 v62, v2
	v_mov_b32_e32 v63, v2
	v_mov_b32_e32 v64, v2
	v_mov_b32_e32 v65, v2
	v_mov_b32_e32 v66, v2
	v_mov_b32_e32 v67, v2
	v_mov_b32_e32 v68, v2
	v_mov_b32_e32 v69, v2
	v_mov_b32_e32 v70, v2
	v_mov_b32_e32 v71, v2
	v_mov_b32_e32 v72, v2
	v_mov_b32_e32 v73, v2
	v_mov_b32_e32 v82, v2
	v_mov_b32_e32 v83, v2
	v_mov_b32_e32 v84, v2
	v_mov_b32_e32 v85, v2
	v_mov_b32_e32 v86, v2
	v_mov_b32_e32 v87, v2
	v_mov_b32_e32 v88, v2
	v_mov_b32_e32 v89, v2
	v_mov_b32_e32 v98, v2
	v_mov_b32_e32 v99, v2
	v_mov_b32_e32 v100, v2
	v_mov_b32_e32 v101, v2
	v_mov_b32_e32 v102, v2
	v_mov_b32_e32 v103, v2
	v_mov_b32_e32 v104, v2
	v_mov_b32_e32 v105, v2
	v_mov_b32_e32 v114, v2
	v_mov_b32_e32 v115, v2
	v_mov_b32_e32 v116, v2
	v_mov_b32_e32 v117, v2
	v_mov_b32_e32 v118, v2
	v_mov_b32_e32 v119, v2
	v_mov_b32_e32 v120, v2
	v_mov_b32_e32 v121, v2
	v_mov_b32_e32 v74, v2
	v_mov_b32_e32 v75, v2
	v_mov_b32_e32 v76, v2
	v_mov_b32_e32 v77, v2
	v_mov_b32_e32 v78, v2
	v_mov_b32_e32 v79, v2
	v_mov_b32_e32 v80, v2
	v_mov_b32_e32 v81, v2
	v_mov_b32_e32 v90, v2
	v_mov_b32_e32 v91, v2
	v_mov_b32_e32 v92, v2
	v_mov_b32_e32 v93, v2
	v_mov_b32_e32 v94, v2
	v_mov_b32_e32 v95, v2
	v_mov_b32_e32 v96, v2
	v_mov_b32_e32 v97, v2
	v_mov_b32_e32 v106, v2
	v_mov_b32_e32 v107, v2
	v_mov_b32_e32 v108, v2
	v_mov_b32_e32 v109, v2
	v_mov_b32_e32 v110, v2
	v_mov_b32_e32 v111, v2
	v_mov_b32_e32 v112, v2
	v_mov_b32_e32 v113, v2
	v_mov_b32_e32 v122, v2
	v_mov_b32_e32 v123, v2
	v_mov_b32_e32 v124, v2
	v_mov_b32_e32 v125, v2
	v_mov_b32_e32 v126, v2
	v_mov_b32_e32 v127, v2
	v_mov_b32_e32 v128, v2
	v_mov_b32_e32 v129, v2
	.p2alignl 6, 3212836864

.LBB0_1514:
	s_add_i32 s17, s44, -2
	s_add_u32 s30, s30, 0x160080
	s_addc_u32 s31, s31, 0
	s_add_u32 s45, s34, 0x100
	v_mov_b32_e32 v2, 0
	s_addc_u32 s89, s35, 0
	s_mov_b32 s34, 0
	v_mov_b32_e32 v3, v2
	v_mov_b32_e32 v4, v2
	v_mov_b32_e32 v5, v2
	v_mov_b32_e32 v6, v2
	v_mov_b32_e32 v7, v2
	v_mov_b32_e32 v8, v2
	v_mov_b32_e32 v9, v2
	v_mov_b32_e32 v10, v2
	v_mov_b32_e32 v11, v2
	v_mov_b32_e32 v12, v2
	v_mov_b32_e32 v13, v2
	v_mov_b32_e32 v14, v2
	v_mov_b32_e32 v15, v2
	v_mov_b32_e32 v16, v2
	v_mov_b32_e32 v17, v2
	v_mov_b32_e32 v18, v2
	v_mov_b32_e32 v19, v2
	v_mov_b32_e32 v20, v2
	v_mov_b32_e32 v21, v2
	v_mov_b32_e32 v22, v2
	v_mov_b32_e32 v23, v2
	v_mov_b32_e32 v24, v2
	v_mov_b32_e32 v25, v2
	v_mov_b32_e32 v26, v2
	v_mov_b32_e32 v27, v2
	v_mov_b32_e32 v28, v2
	v_mov_b32_e32 v29, v2
	v_mov_b32_e32 v30, v2
	v_mov_b32_e32 v31, v2
	v_mov_b32_e32 v32, v2
	v_mov_b32_e32 v33, v2
	v_mov_b32_e32 v70, v2
	v_mov_b32_e32 v71, v2
	v_mov_b32_e32 v72, v2
	v_mov_b32_e32 v73, v2
	v_mov_b32_e32 v74, v2
	v_mov_b32_e32 v75, v2
	v_mov_b32_e32 v76, v2
	v_mov_b32_e32 v77, v2
	v_mov_b32_e32 v78, v2
	v_mov_b32_e32 v79, v2
	v_mov_b32_e32 v80, v2
	v_mov_b32_e32 v81, v2
	v_mov_b32_e32 v82, v2
	v_mov_b32_e32 v83, v2
	v_mov_b32_e32 v84, v2
	v_mov_b32_e32 v85, v2
	v_mov_b32_e32 v86, v2
	v_mov_b32_e32 v87, v2
	v_mov_b32_e32 v88, v2
	v_mov_b32_e32 v89, v2
	v_mov_b32_e32 v90, v2
	v_mov_b32_e32 v91, v2
	v_mov_b32_e32 v92, v2
	v_mov_b32_e32 v93, v2
	v_mov_b32_e32 v94, v2
	v_mov_b32_e32 v95, v2
	v_mov_b32_e32 v96, v2
	v_mov_b32_e32 v97, v2
	v_mov_b32_e32 v34, v2
	v_mov_b32_e32 v35, v2
	v_mov_b32_e32 v36, v2
	v_mov_b32_e32 v37, v2
	v_mov_b32_e32 v98, v2
	v_mov_b32_e32 v99, v2
	v_mov_b32_e32 v100, v2
	v_mov_b32_e32 v101, v2
	v_mov_b32_e32 v38, v2
	v_mov_b32_e32 v39, v2
	v_mov_b32_e32 v40, v2
	v_mov_b32_e32 v41, v2
	v_mov_b32_e32 v42, v2
	v_mov_b32_e32 v43, v2
	v_mov_b32_e32 v44, v2
	v_mov_b32_e32 v45, v2
	v_mov_b32_e32 v46, v2
	v_mov_b32_e32 v47, v2
	v_mov_b32_e32 v48, v2
	v_mov_b32_e32 v49, v2
	v_mov_b32_e32 v50, v2
	v_mov_b32_e32 v51, v2
	v_mov_b32_e32 v52, v2
	v_mov_b32_e32 v53, v2
	v_mov_b32_e32 v54, v2
	s_waitcnt lgkmcnt(0)
	v_mov_b32_e32 v55, v2
	v_mov_b32_e32 v56, v2
	v_mov_b32_e32 v57, v2
	v_mov_b32_e32 v58, v2
	v_mov_b32_e32 v59, v2
	v_mov_b32_e32 v60, v2
	v_mov_b32_e32 v61, v2
	v_mov_b32_e32 v62, v2
	v_mov_b32_e32 v63, v2
	v_mov_b32_e32 v64, v2
	v_mov_b32_e32 v65, v2
	v_mov_b32_e32 v102, v2
	v_mov_b32_e32 v103, v2
	v_mov_b32_e32 v104, v2
	v_mov_b32_e32 v105, v2
	v_mov_b32_e32 v106, v2
	v_mov_b32_e32 v107, v2
	v_mov_b32_e32 v108, v2
	v_mov_b32_e32 v109, v2
	v_mov_b32_e32 v110, v2
	v_mov_b32_e32 v111, v2
	v_mov_b32_e32 v112, v2
	v_mov_b32_e32 v113, v2
	v_mov_b32_e32 v114, v2
	v_mov_b32_e32 v115, v2
	v_mov_b32_e32 v116, v2
	v_mov_b32_e32 v117, v2
	v_mov_b32_e32 v118, v2
	v_mov_b32_e32 v119, v2
	v_mov_b32_e32 v120, v2
	v_mov_b32_e32 v121, v2
	v_mov_b32_e32 v122, v2
	v_mov_b32_e32 v123, v2
	v_mov_b32_e32 v124, v2
	v_mov_b32_e32 v125, v2
	v_mov_b32_e32 v126, v2
	v_mov_b32_e32 v127, v2
	v_mov_b32_e32 v128, v2
	v_mov_b32_e32 v129, v2
	v_mov_b32_e32 v66, v2
	v_mov_b32_e32 v67, v2
	v_mov_b32_e32 v68, v2
	v_mov_b32_e32 v69, v2
	.p2alignl 6, 3212836864
